# scan item start: decay constant no longer waited for before the tile loads are issued (one memory round trip less per item)
# baseline (speedup 1.0000x reference)
; __device__ __forceinline__ void scan_loadw(PP p, int dir, int n, int ct, int l31, int hl, ScanW& w) {
;     unsigned chv = (unsigned)(32 * ct + l31); asm volatile("" : "+v"(chv));
;     const unsigned ch = (unsigned)(dir * 512 + 64 * n) + chv;
;     w.ba = p->lru_b_a[ch]; w.bi = p->lru_b_i[ch];
;     w.sp8l2 = ((const float*)(p->ws + WS_SP8))[ch] * 1.4426950408889634f;
;     const bf16_t* wa_b = (const bf16_t*)(p->ws + WS_LRU) + (size_t)((dir * 2 + 0) * 8 + n) * 4096;
;     const bf16_t* wi_b = (const bf16_t*)(p->ws + WS_LRU) + (size_t)((dir * 2 + 1) * 8 + n) * 4096;
;     const unsigned lo = chv * 64u + 8u * (unsigned)hl;
; #pragma unroll
;     for (int st = 0; st < 4; ++st) { w.wfa[st] = *(const bf16x8*)(wa_b + lo + 16 * st); w.wfi[st] = *(const bf16x8*)(wi_b + lo + 16 * st); }
; }
.LBB0_330:
	s_cmpk_lt_i32 s78, 0x200
	s_cselect_b64 s[22:23], -1, 0
	s_cmpk_gt_i32 s78, 0x1ff
	s_cselect_b64 s[28:29], -1, 0
	s_and_b64 vcc, exec, s[28:29]
	s_cbranch_vccnz .LBB0_332
	v_mov_b32_e32 v38, v148
	s_load_dwordx2 s[4:5], s[8:9], 0x58
	s_load_dwordx2 s[30:31], s[8:9], 0x68
	v_add_u32_e32 v0, s33, v38
	v_lshlrev_b64 v[34:35], 2, v[0:1]
	v_lshl_or_b32 v0, v38, 6, v149
	s_waitcnt lgkmcnt(0)
	v_lshl_add_u64 v[36:37], s[4:5], 0, v[34:35]
	global_load_dword v192, v[36:37], off
	v_lshl_add_u64 v[36:37], s[30:31], 0, v[34:35]
	global_load_dword v191, v[36:37], off
	v_lshl_add_u64 v[34:35], s[12:13], 0, v[34:35]
	v_lshlrev_b64 v[36:37], 1, v[0:1]
	v_lshl_add_u64 v[38:39], s[14:15], 0, v[36:37]
	v_lshl_add_u64 v[36:37], s[18:19], 0, v[36:37]
	global_load_dword v100, v[34:35], off
	global_load_dwordx4 v[114:117], v[38:39], off
	global_load_dwordx4 v[118:121], v[38:39], off offset:32
	global_load_dwordx4 v[122:125], v[38:39], off offset:64
	global_load_dwordx4 v[126:129], v[36:37], off offset:32
	global_load_dwordx4 v[130:133], v[36:37], off offset:64
	global_load_dwordx4 v[134:137], v[36:37], off
	global_load_dwordx4 v[138:141], v[38:39], off offset:96
	global_load_dwordx4 v[142:145], v[36:37], off offset:96
; __device__ __forceinline__ int tid_opaque(int wv) { return wv * 64 + lane_fresh(); }
; __device__ __forceinline__ void scan_loadw(PP p, int dir, int n, int ct, int l31, int hl, ScanW& w) {
;     ...
;     w.sp8l2 = ((const float*)(p->ws + WS_SP8))[ch] * 1.4426950408889634f;
; __device__ __forceinline__ void scan_mfma(PP p, unsigned char* shm, int wv) {
;     ...
;         {
;             const int tid = tid_opaque(wv);
;             bf16_t* raw = (bf16_t*)(shm + 66560);
; #pragma unroll
;             for (int i = 0; i < 9; ++i) {
;                 const int piece = tid + 512 * i;
;                 if (piece < 67 * 64) {
;                     const int row = piece >> 6, c8 = piece & 63, tt = t0 - 2 + row;
;                     u32x4 v = {0u, 0u, 0u, 0u};
;                     if (tt >= 0 && tt < seqlen) v = *(const u32x4*)(proj + (size_t)(seqbase + tt) * DIN + 8 * c8);
;                     *(u32x4*)(raw + row * 512 + 8 * c8) = v;
;                 }
;             }
.LBB0_332:
	s_add_i32 s4, s78, 0xfffffe00
	s_lshr_b32 s5, s4, 2
	s_addk_i32 s5, 0x200
	s_lshl_b32 s4, s78, 6
	s_lshl_b32 s35, s5, 6
	s_and_b32 s34, s4, 0x3fc0
	s_and_b32 s36, s35, 0xc0
	s_and_b64 s[30:31], s[22:23], exec
	s_mov_b32 s30, -1
	s_cselect_b32 s38, s34, s36
	v_mbcnt_lo_u32_b32 v0, s30, 0
	v_mbcnt_hi_u32_b32 v0, s30, v0
	v_add_u32_e32 v54, s33, v0
	v_lshlrev_b32_e32 v0, 4, v0
	s_cselect_b32 s4, s4, s35
	v_and_b32_e32 v0, 0x3f0, v0
	s_cselect_b32 s37, 0x4000, s64
	s_sub_i32 s36, s4, s38
	s_add_i32 s38, s38, -2
	v_lshl_add_u64 v[38:39], s[10:11], 0, v[0:1]
	v_add_u32_e32 v0, s65, v0
	s_mov_b64 s[30:31], exec
	v_ashrrev_i32_e32 v95, 6, v54
	v_add_u32_e32 v96, s38, v95
	v_lshl_add_u32 v86, v95, 10, v0
	v_mov_b32_e32 v2, 0
	v_mov_b32_e32 v3, 0
	v_mov_b32_e32 v4, 0
	v_mov_b32_e32 v5, 0
	v_cmp_gt_u32_e32 vcc, s37, v96
	v_cmp_gt_i32_e64 s[34:35], s66, v54
	s_and_b64 vcc, vcc, s[34:35]
	s_and_b64 exec, s[30:31], vcc
	v_add_u32_e32 v97, s36, v96
	v_mad_i64_i32 v[98:99], s[40:41], v97, s67, v[38:39]
	global_load_dwordx4 v[2:5], v[98:99], off
	s_mov_b64 exec, s[30:31]
	v_add_u32_e32 v95, 0x200, v54
	v_ashrrev_i32_e32 v95, 6, v95
	v_add_u32_e32 v96, s38, v95
	v_lshl_add_u32 v87, v95, 10, v0
	v_mov_b32_e32 v6, 0
	v_mov_b32_e32 v7, 0
	v_mov_b32_e32 v8, 0
	v_mov_b32_e32 v9, 0
	v_cmp_gt_u32_e32 vcc, s37, v96
	v_cmp_gt_i32_e64 s[34:35], s68, v54
	s_and_b64 vcc, vcc, s[34:35]
	s_and_b64 exec, s[30:31], vcc
	v_add_u32_e32 v97, s36, v96
	v_mad_i64_i32 v[98:99], s[40:41], v97, s67, v[38:39]
	global_load_dwordx4 v[6:9], v[98:99], off
	s_mov_b64 exec, s[30:31]
	v_add_u32_e32 v95, 0x400, v54
	v_ashrrev_i32_e32 v95, 6, v95
	v_add_u32_e32 v96, s38, v95
	v_lshl_add_u32 v88, v95, 10, v0
	v_mov_b32_e32 v10, 0
	v_mov_b32_e32 v11, 0
	v_mov_b32_e32 v12, 0
	v_mov_b32_e32 v13, 0
	v_cmp_gt_u32_e32 vcc, s37, v96
	v_cmp_gt_i32_e64 s[34:35], s69, v54
	s_and_b64 vcc, vcc, s[34:35]
	s_and_b64 exec, s[30:31], vcc
	v_add_u32_e32 v97, s36, v96
	v_mad_i64_i32 v[98:99], s[40:41], v97, s67, v[38:39]
	global_load_dwordx4 v[10:13], v[98:99], off
	s_mov_b64 exec, s[30:31]
	v_add_u32_e32 v95, 0x600, v54
	v_ashrrev_i32_e32 v95, 6, v95
	v_add_u32_e32 v96, s38, v95
	v_lshl_add_u32 v89, v95, 10, v0
	v_mov_b32_e32 v14, 0
	v_mov_b32_e32 v15, 0
	v_mov_b32_e32 v16, 0
	v_mov_b32_e32 v17, 0
	v_cmp_gt_u32_e32 vcc, s37, v96
	v_cmp_gt_i32_e64 s[34:35], s70, v54
	s_and_b64 vcc, vcc, s[34:35]
	s_and_b64 exec, s[30:31], vcc
	v_add_u32_e32 v97, s36, v96
	v_mad_i64_i32 v[98:99], s[40:41], v97, s67, v[38:39]
	global_load_dwordx4 v[14:17], v[98:99], off
	s_mov_b64 exec, s[30:31]
	v_add_u32_e32 v95, 0x800, v54
	v_ashrrev_i32_e32 v95, 6, v95
	v_add_u32_e32 v96, s38, v95
	v_lshl_add_u32 v90, v95, 10, v0
	v_mov_b32_e32 v18, 0
	v_mov_b32_e32 v19, 0
	v_mov_b32_e32 v20, 0
	v_mov_b32_e32 v21, 0
	v_cmp_gt_u32_e32 vcc, s37, v96
	v_cmp_gt_i32_e64 s[34:35], s71, v54
	s_and_b64 vcc, vcc, s[34:35]
	s_and_b64 exec, s[30:31], vcc
	v_add_u32_e32 v97, s36, v96
	v_mad_i64_i32 v[98:99], s[40:41], v97, s67, v[38:39]
	global_load_dwordx4 v[18:21], v[98:99], off
	s_mov_b64 exec, s[30:31]
	v_add_u32_e32 v95, 0xa00, v54
	v_ashrrev_i32_e32 v95, 6, v95
	v_add_u32_e32 v96, s38, v95
	v_lshl_add_u32 v91, v95, 10, v0
	v_mov_b32_e32 v22, 0
	v_mov_b32_e32 v23, 0
	v_mov_b32_e32 v24, 0
	v_mov_b32_e32 v25, 0
	v_cmp_gt_u32_e32 vcc, s37, v96
	v_cmp_gt_i32_e64 s[34:35], s72, v54
	s_and_b64 vcc, vcc, s[34:35]
	s_and_b64 exec, s[30:31], vcc
	v_add_u32_e32 v97, s36, v96
	v_mad_i64_i32 v[98:99], s[40:41], v97, s67, v[38:39]
	global_load_dwordx4 v[22:25], v[98:99], off
	s_mov_b64 exec, s[30:31]
	v_add_u32_e32 v95, 0xc00, v54
	v_ashrrev_i32_e32 v95, 6, v95
	v_add_u32_e32 v96, s38, v95
	v_lshl_add_u32 v92, v95, 10, v0
	v_mov_b32_e32 v26, 0
	v_mov_b32_e32 v27, 0
	v_mov_b32_e32 v28, 0
	v_mov_b32_e32 v29, 0
	v_cmp_gt_u32_e32 vcc, s37, v96
	v_cmp_gt_i32_e64 s[34:35], s73, v54
	s_and_b64 vcc, vcc, s[34:35]
	s_and_b64 exec, s[30:31], vcc
	v_add_u32_e32 v97, s36, v96
	v_mad_i64_i32 v[98:99], s[40:41], v97, s67, v[38:39]
	global_load_dwordx4 v[26:29], v[98:99], off
	s_mov_b64 exec, s[30:31]
	v_add_u32_e32 v95, 0xe00, v54
	v_ashrrev_i32_e32 v95, 6, v95
	v_add_u32_e32 v96, s38, v95
	v_lshl_add_u32 v93, v95, 10, v0
	v_mov_b32_e32 v30, 0
	v_mov_b32_e32 v31, 0
	v_mov_b32_e32 v32, 0
	v_mov_b32_e32 v33, 0
	v_cmp_gt_u32_e32 vcc, s37, v96
	v_cmp_gt_i32_e64 s[34:35], s74, v54
	s_and_b64 vcc, vcc, s[34:35]
	s_and_b64 exec, s[30:31], vcc
	v_add_u32_e32 v97, s36, v96
	v_mad_i64_i32 v[98:99], s[40:41], v97, s67, v[38:39]
	global_load_dwordx4 v[30:33], v[98:99], off
	s_mov_b64 exec, s[30:31]
	v_add_u32_e32 v95, 0x1000, v54
	v_ashrrev_i32_e32 v95, 6, v95
	v_add_u32_e32 v96, s38, v95
	v_lshl_add_u32 v94, v95, 10, v0
	v_mov_b32_e32 v82, 0
	v_mov_b32_e32 v83, 0
	v_mov_b32_e32 v84, 0
	v_mov_b32_e32 v85, 0
	v_cmp_gt_u32_e32 vcc, s37, v96
	v_cmp_gt_i32_e64 s[34:35], s61, v54
	s_and_b64 vcc, vcc, s[34:35]
	s_and_b64 exec, s[30:31], vcc
	v_add_u32_e32 v97, s36, v96
	v_mad_i64_i32 v[98:99], s[40:41], v97, s67, v[38:39]
	global_load_dwordx4 v[82:85], v[98:99], off
	s_mov_b64 exec, s[30:31]
	s_waitcnt vmcnt(0)
	s_cmp_lg_u64 s[22:23], 0
	s_cbranch_scc0 .Lscan_nomul0
	v_mul_f32_e32 v194, 0x3fb8aa3b, v100
.Lscan_nomul0:
	v_cmp_gt_i32_e32 vcc, s66, v54
	s_and_b64 exec, s[30:31], vcc
	ds_write_b128 v86, v[2:5]
	v_cmp_gt_i32_e32 vcc, s68, v54
	s_and_b64 exec, s[30:31], vcc
	ds_write_b128 v87, v[6:9]
	v_cmp_gt_i32_e32 vcc, s69, v54
	s_and_b64 exec, s[30:31], vcc
	ds_write_b128 v88, v[10:13]
	v_cmp_gt_i32_e32 vcc, s70, v54
	s_and_b64 exec, s[30:31], vcc
	ds_write_b128 v89, v[14:17]
	v_cmp_gt_i32_e32 vcc, s71, v54
	s_and_b64 exec, s[30:31], vcc
	ds_write_b128 v90, v[18:21]
	v_cmp_gt_i32_e32 vcc, s72, v54
	s_and_b64 exec, s[30:31], vcc
	ds_write_b128 v91, v[22:25]
	v_cmp_gt_i32_e32 vcc, s73, v54
	s_and_b64 exec, s[30:31], vcc
	ds_write_b128 v92, v[26:29]
	v_cmp_gt_i32_e32 vcc, s74, v54
	s_and_b64 exec, s[30:31], vcc
	ds_write_b128 v93, v[30:33]
	v_cmp_gt_i32_e32 vcc, s61, v54
	s_and_b64 exec, s[30:31], vcc
	ds_write_b128 v94, v[82:85]
	s_mov_b64 exec, s[30:31]
